# static s_setprio 1 for waves 4-7 during the differential-attention phase (reset at its exit)
# speedup vs baseline: 1.1172x; 1.0014x over previous
.LBB0_384:
	v_readlane_b32 s100, v254, 25
	s_nop 3
	s_cmp_ge_u32 s100, 4
	s_cbranch_scc0 .Lprio_skip
	s_setprio 1

.LBB0_469:
	s_setprio 0
	s_waitcnt vmcnt(0)
	v_readlane_b32 s66, v254, 22
	v_readlane_b32 s67, v254, 23
	v_readlane_b32 s72, v255, 2
	v_readlane_b32 s52, v254, 55
	s_and_b64 vcc, exec, s[66:67]
	v_readlane_b32 s70, v255, 10
	v_readlane_b32 s73, v255, 3
	v_readlane_b32 s53, v254, 56
	v_readlane_b32 s42, v254, 50
	s_waitcnt vmcnt(63) expcnt(7) lgkmcnt(15)
	s_barrier
	v_readlane_b32 s43, v254, 51
	s_cbranch_vccnz .LBB0_523
	v_mbcnt_lo_u32_b32 v0, -1, 0
	v_mbcnt_hi_u32_b32 v0, -1, v0
	s_nop 0
	v_cmp_eq_u32_e32 vcc, 0, v0
	s_and_saveexec_b64 s[0:1], vcc
	s_cbranch_execz .LBB0_522
	s_add_i32 s2, 0, 0x21000
	v_mov_b32_e32 v0, s2
	s_waitcnt vmcnt(0) expcnt(0) lgkmcnt(0)
	ds_read_b32 v2, v0
	s_add_i32 s2, 0, 0x21004
	v_mov_b32_e32 v0, s2
	ds_read_b32 v0, v0
	s_waitcnt lgkmcnt(1)
	v_cmp_ne_u32_e32 vcc, 0, v2
	s_cbranch_vccnz .LBB0_486
	s_add_u32 s4, s74, 0xfa00200
	s_addc_u32 s5, s75, 0
	s_add_u32 s6, s74, 0xfa00400
	s_addc_u32 s7, s75, 0
	s_add_u32 s8, s74, 0xfa00500
	s_addc_u32 s9, s75, 0
	s_add_u32 s10, s74, 0xfa00600
	s_addc_u32 s11, s75, 0
	s_add_u32 s12, s74, 0xfa00700
	s_addc_u32 s13, s75, 0
	s_add_u32 s14, s74, 0xfa00800
	s_addc_u32 s15, s75, 0
	s_add_u32 s16, s74, 0xfa00900
	s_addc_u32 s17, s75, 0
	s_add_u32 s18, s74, 0xfa00a00
	s_addc_u32 s19, s75, 0
	s_add_u32 s20, s74, 0xfa00b00
	s_addc_u32 s21, s75, 0
	s_add_u32 s22, s74, 0xfa00c00
	s_addc_u32 s23, s75, 0
	s_add_u32 s24, s74, 0xfa00d00
	s_addc_u32 s25, s75, 0
	s_add_u32 s26, s74, 0xfa00e00
	s_addc_u32 s27, s75, 0
	s_add_u32 s28, s74, 0xfa00f00
	s_addc_u32 s29, s75, 0
	s_add_u32 s30, s74, 0xfa01000
	s_addc_u32 s31, s75, 0
	s_add_u32 s34, s74, 0xfa01100
	s_addc_u32 s35, s75, 0
	s_add_u32 s36, s74, 0xfa01200
	v_readlane_b32 s2, v254, 4
	s_addc_u32 s37, s75, 0
	s_mul_i32 s2, s79, s2
	s_add_u32 s38, s74, 0xfa01300
	s_mul_i32 s2, s2, s78
	s_addc_u32 s39, s75, 0
	s_mov_b32 s3, 1
	v_mov_b32_e32 v16, 0
	s_branch .LBB0_474
